# P0 weight-convert calls start at rotated workgroup indices (busiest WG 28 tiles instead of 32)
# baseline (speedup 1.0000x reference)
; DEVI int otid() { int t = threadIdx.x; asm volatile("" : "+v"(t)); return t; }
; DEVI int obid() { int t = blockIdx.x; asm volatile("" : "+s"(t)); return t; }
; __device__ __forceinline__ void wconv(unsigned char* lds, const float* __restrict__ src, bf16_t* __restrict__ dst, int K, int Nsrc, int Ndst, int mode, int nbatch) {
;   float* tile = (float*)lds;
;   const int tid = otid();
;   const int tk = K >> 6, tn = Ndst >> 6, per = tk * tn, total = per * nbatch;
;   for (int it = obid(); it < total; it += gridDim.x) {
;     const int bi = it / per, rem = it - bi * per, kt = rem / tn, nt = rem - kt * tn;
;     const float* s = src + (size_t)bi * K * Nsrc; bf16_t* d = dst + (size_t)bi * Ndst * K;
;     const int nn = tid & 63, dcol = nt * 64 + nn;
;     int scol; float scale = 1.f;
;     if (mode == 0) scol = dcol < Nsrc ? dcol : -1;
;     else {
;       if (dcol < 2048) { scol = dcol; if (dcol >= 512 && dcol < 1024) scale = 0.08838834764831845f; }
;       else if (dcol < 3072) scol = dcol - 2048 + 3080;
;       else if (dcol < 4096) scol = dcol - 3072 + 2048;
;       else if (dcol < 5120) scol = dcol - 4096 + 4104;
;       else if (dcol < 5128) scol = dcol - 5120 + 3072;
;       else scol = -1;
;     }
;     __syncthreads();
; #pragma unroll
;     for (int i = 0; i < 8; ++i) {
;       const int kk = (tid >> 6) + 8 * i;
;       float v = 0.f; if (scol >= 0) v = s[(size_t)(kt * 64 + kk) * Nsrc + scol] * scale;
;       tile[kk * 65 + nn] = v;
; __global__ void __launch_bounds__(NT, 2) fwd_megakernel(Params p) {
;     ...
;   wconv(smem, p.od_w_in, (bf16_t*)(ws + OFF_WINO), 1024, 2216, 2304, 0, 1);
.LBB0_72:
	s_load_dwordx16 s[64:79], s[0:1], 0x80
	v_readlane_b32 s0, v253, 2
	v_writelane_b32 v254, s18, 0
	v_readlane_b32 s2, v253, 4
	v_readlane_b32 s3, v253, 5
	v_writelane_b32 v254, s19, 1
	s_add_u32 s0, s2, 0x2e80000
	v_writelane_b32 v254, s0, 2
	s_addc_u32 s0, s3, 0
	v_mov_b32_e32 v2, v128
	s_mov_b32 s8, s20
	s_cmp_lg_u32 s52, 0x100
	s_cbranch_scc1 .Lp0sh_1079
	s_add_i32 s8, s20, 0xc0
	s_and_b32 s8, s8, 0xff
.Lp0sh_1079:
	s_waitcnt lgkmcnt(0)
	s_barrier
	v_writelane_b32 v254, s0, 3
	s_cmpk_gt_i32 s8, 0x23f
	v_readlane_b32 s1, v253, 3
	s_cbranch_scc1 .LBB0_83
	v_and_b32_e32 v1, 63, v2
	v_ashrrev_i32_e32 v8, 6, v2
	v_ashrrev_i32_e32 v9, 3, v2
	v_lshlrev_b32_e32 v2, 3, v2
	v_and_b32_e32 v2, 56, v2
	v_lshlrev_b32_e32 v5, 2, v9
	s_movk_i32 s0, 0x104
	v_mul_u32_u24_e32 v6, 0x104, v2
	v_lshlrev_b32_e32 v4, 2, v1
	v_mov_b32_e32 v3, 0
	v_mul_lo_u32 v7, v8, s0
	v_add_u32_e32 v15, v5, v6
	v_add_u32_e32 v10, 32, v8
	v_add_u32_e32 v11, 40, v8
	v_add_u32_e32 v12, 48, v8
	v_add_u32_e32 v13, 56, v8
	s_movk_i32 s9, 0x8a8
	v_add_u32_e32 v14, v4, v7
	s_movk_i32 s10, 0x22a0
	v_lshlrev_b32_e32 v4, 1, v2
	v_mov_b32_e32 v5, v3
	v_add_u32_e32 v16, 0x400, v15
	s_branch .LBB0_75

; DEVI int otid() { int t = threadIdx.x; asm volatile("" : "+v"(t)); return t; }
; DEVI int obid() { int t = blockIdx.x; asm volatile("" : "+s"(t)); return t; }
; __device__ __forceinline__ void wconv(unsigned char* lds, const float* __restrict__ src, bf16_t* __restrict__ dst, int K, int Nsrc, int Ndst, int mode, int nbatch) {
;   float* tile = (float*)lds;
;   const int tid = otid();
;   const int tk = K >> 6, tn = Ndst >> 6, per = tk * tn, total = per * nbatch;
;   for (int it = obid(); it < total; it += gridDim.x) {
;     const int bi = it / per, rem = it - bi * per, kt = rem / tn, nt = rem - kt * tn;
;     const float* s = src + (size_t)bi * K * Nsrc; bf16_t* d = dst + (size_t)bi * Ndst * K;
;     const int nn = tid & 63, dcol = nt * 64 + nn;
;     int scol; float scale = 1.f;
;     if (mode == 0) scol = dcol < Nsrc ? dcol : -1;
;     else {
;       if (dcol < 2048) { scol = dcol; if (dcol >= 512 && dcol < 1024) scale = 0.08838834764831845f; }
;       else if (dcol < 3072) scol = dcol - 2048 + 3080;
;       else if (dcol < 4096) scol = dcol - 3072 + 2048;
;       else if (dcol < 5120) scol = dcol - 4096 + 4104;
;       else if (dcol < 5128) scol = dcol - 5120 + 3072;
;       else scol = -1;
;     }
;     __syncthreads();
; #pragma unroll
;     for (int i = 0; i < 8; ++i) {
;       const int kk = (tid >> 6) + 8 * i;
;       float v = 0.f; if (scol >= 0) v = s[(size_t)(kt * 64 + kk) * Nsrc + scol] * scale;
;       tile[kk * 65 + nn] = v;
; __global__ void __launch_bounds__(NT, 2) fwd_megakernel(Params p) {
;     ...
;   wconv(smem, p.od_w_uq, (bf16_t*)(ws + OFF_WUQ), 384, 768, 768, 0, 1);
.LBB0_83:
	v_readlane_b32 s0, v253, 2
	v_readlane_b32 s2, v253, 4
	v_readlane_b32 s3, v253, 5
	s_add_u32 s0, s2, 0x3300000
	v_writelane_b32 v254, s0, 4
	s_addc_u32 s0, s3, 0
	v_writelane_b32 v254, s0, 5
	v_mov_b32_e32 v2, v128
	s_mov_b32 s10, s20
	s_cmp_lg_u32 s52, 0x100
	s_cbranch_scc1 .Lp0sh_1277
	s_add_i32 s10, s20, 0x80
	s_and_b32 s10, s10, 0xff
.Lp0sh_1277:
	v_readlane_b32 s24, v254, 0
	s_barrier
	s_cmpk_gt_i32 s10, 0x47
	v_readlane_b32 s25, v254, 1
	v_readlane_b32 s1, v253, 3
	s_cbranch_scc1 .LBB0_94
	v_and_b32_e32 v1, 63, v2
	v_ashrrev_i32_e32 v8, 6, v2
	v_ashrrev_i32_e32 v9, 3, v2
	v_lshlrev_b32_e32 v2, 3, v2
	v_and_b32_e32 v2, 56, v2
	v_lshlrev_b32_e32 v5, 2, v9
	s_movk_i32 s0, 0x104
	v_mul_u32_u24_e32 v6, 0x104, v2
	v_lshlrev_b32_e32 v4, 2, v1
	v_mov_b32_e32 v3, 0
	v_mul_lo_u32 v7, v8, s0
	v_add_u32_e32 v15, v5, v6
	v_add_u32_e32 v10, 32, v8
	v_add_u32_e32 v11, 40, v8
	v_add_u32_e32 v12, 48, v8
	v_add_u32_e32 v13, 56, v8
	s_movk_i32 s11, 0x300
	v_add_u32_e32 v14, v4, v7
	s_movk_i32 s12, 0xc00
	v_lshlrev_b32_e32 v4, 1, v2
	v_mov_b32_e32 v5, v3
	v_add_u32_e32 v16, 0x400, v15
	s_branch .LBB0_86

; DEVI int otid() { int t = threadIdx.x; asm volatile("" : "+v"(t)); return t; }
; DEVI int obid() { int t = blockIdx.x; asm volatile("" : "+s"(t)); return t; }
; __device__ __forceinline__ void wconv(unsigned char* lds, const float* __restrict__ src, bf16_t* __restrict__ dst, int K, int Nsrc, int Ndst, int mode, int nbatch) {
;   float* tile = (float*)lds;
;   const int tid = otid();
;   const int tk = K >> 6, tn = Ndst >> 6, per = tk * tn, total = per * nbatch;
;   for (int it = obid(); it < total; it += gridDim.x) {
;     const int bi = it / per, rem = it - bi * per, kt = rem / tn, nt = rem - kt * tn;
;     const float* s = src + (size_t)bi * K * Nsrc; bf16_t* d = dst + (size_t)bi * Ndst * K;
;     const int nn = tid & 63, dcol = nt * 64 + nn;
;     int scol; float scale = 1.f;
;     if (mode == 0) scol = dcol < Nsrc ? dcol : -1;
;     else {
;       if (dcol < 2048) { scol = dcol; if (dcol >= 512 && dcol < 1024) scale = 0.08838834764831845f; }
;       else if (dcol < 3072) scol = dcol - 2048 + 3080;
;       else if (dcol < 4096) scol = dcol - 3072 + 2048;
;       else if (dcol < 5120) scol = dcol - 4096 + 4104;
;       else if (dcol < 5128) scol = dcol - 5120 + 3072;
;       else scol = -1;
;     }
;     __syncthreads();
; #pragma unroll
;     for (int i = 0; i < 8; ++i) {
;       const int kk = (tid >> 6) + 8 * i;
;       float v = 0.f; if (scol >= 0) v = s[(size_t)(kt * 64 + kk) * Nsrc + scol] * scale;
;       tile[kk * 65 + nn] = v;
; __global__ void __launch_bounds__(NT, 2) fwd_megakernel(Params p) {
;     ...
;   wconv(smem, p.od_w_ukv, (bf16_t*)(ws + OFF_WUKV), 256, 1024, 1024, 0, 1);
.LBB0_94:
	v_readlane_b32 s0, v253, 2
	v_readlane_b32 s2, v253, 4
	v_readlane_b32 s3, v253, 5
	s_add_u32 s0, s2, 0x3390000
	v_writelane_b32 v254, s0, 6
	s_addc_u32 s0, s3, 0
	v_mov_b32_e32 v2, v128
	s_mov_b32 s10, s20
	s_cmp_lg_u32 s52, 0x100
	s_cbranch_scc1 .Lp0sh_1473
	s_add_i32 s10, s20, 0x38
	s_and_b32 s10, s10, 0xff
.Lp0sh_1473:
	s_barrier
	v_writelane_b32 v254, s0, 7
	s_cmp_gt_i32 s10, 63
	v_readlane_b32 s1, v253, 3
	s_cbranch_scc1 .LBB0_105
	v_and_b32_e32 v1, 63, v2
	v_ashrrev_i32_e32 v8, 6, v2
	v_ashrrev_i32_e32 v9, 3, v2
	v_lshlrev_b32_e32 v2, 3, v2
	v_and_b32_e32 v2, 56, v2
	v_lshlrev_b32_e32 v5, 2, v9
	s_movk_i32 s0, 0x104
	v_mul_u32_u24_e32 v6, 0x104, v2
	v_lshlrev_b32_e32 v4, 2, v1
	v_mov_b32_e32 v3, 0
	v_mul_lo_u32 v7, v8, s0
	v_add_u32_e32 v15, v5, v6
	v_add_u32_e32 v10, 32, v8
	v_add_u32_e32 v11, 40, v8
	v_add_u32_e32 v12, 48, v8
	v_add_u32_e32 v13, 56, v8
	s_lshl_b32 s11, s10, 6
	s_lshl_b32 s12, s52, 6
	s_movk_i32 s13, 0x400
	v_add_u32_e32 v14, v4, v7
	v_lshlrev_b32_e32 v4, 1, v2
	v_mov_b32_e32 v5, v3
	v_add_u32_e32 v16, 0x400, v15
	s_branch .LBB0_97

; DEVI int otid() { int t = threadIdx.x; asm volatile("" : "+v"(t)); return t; }
; DEVI int obid() { int t = blockIdx.x; asm volatile("" : "+s"(t)); return t; }
; __device__ __forceinline__ void wconv(unsigned char* lds, const float* __restrict__ src, bf16_t* __restrict__ dst, int K, int Nsrc, int Ndst, int mode, int nbatch) {
;   float* tile = (float*)lds;
;   const int tid = otid();
;   const int tk = K >> 6, tn = Ndst >> 6, per = tk * tn, total = per * nbatch;
;   for (int it = obid(); it < total; it += gridDim.x) {
;     const int bi = it / per, rem = it - bi * per, kt = rem / tn, nt = rem - kt * tn;
;     const float* s = src + (size_t)bi * K * Nsrc; bf16_t* d = dst + (size_t)bi * Ndst * K;
;     const int nn = tid & 63, dcol = nt * 64 + nn;
;     int scol; float scale = 1.f;
;     if (mode == 0) scol = dcol < Nsrc ? dcol : -1;
;     else {
;       if (dcol < 2048) { scol = dcol; if (dcol >= 512 && dcol < 1024) scale = 0.08838834764831845f; }
;       else if (dcol < 3072) scol = dcol - 2048 + 3080;
;       else if (dcol < 4096) scol = dcol - 3072 + 2048;
;       else if (dcol < 5120) scol = dcol - 4096 + 4104;
;       else if (dcol < 5128) scol = dcol - 5120 + 3072;
;       else scol = -1;
;     }
;     __syncthreads();
; #pragma unroll
;     for (int i = 0; i < 8; ++i) {
;       const int kk = (tid >> 6) + 8 * i;
;       float v = 0.f; if (scol >= 0) v = s[(size_t)(kt * 64 + kk) * Nsrc + scol] * scale;
;       tile[kk * 65 + nn] = v;
; __global__ void __launch_bounds__(NT, 2) fwd_megakernel(Params p) {
;     ...
;   wconv(smem, p.ev_w_ra, (bf16_t*)(ws + OFF_WRA), 128, 128, 128, 0, 8);
.LBB0_116:
	v_readlane_b32 s0, v253, 2
	v_readlane_b32 s2, v253, 4
	v_readlane_b32 s3, v253, 5
	s_add_u32 s0, s2, 0x3610000
	v_writelane_b32 v254, s0, 10
	s_addc_u32 s0, s3, 0
	v_mov_b32_e32 v2, v128
	s_mov_b32 s10, s20
	s_cmp_lg_u32 s52, 0x100
	s_cbranch_scc1 .Lp0sh_1934
	s_add_i32 s10, s20, 0xf8
	s_and_b32 s10, s10, 0xff
.Lp0sh_1934:
	s_barrier
	v_writelane_b32 v254, s0, 12
	s_cmp_gt_i32 s10, 31
	v_readlane_b32 s1, v253, 3
	s_cbranch_scc1 .LBB0_127
	v_and_b32_e32 v1, 63, v2
	v_ashrrev_i32_e32 v8, 6, v2
	v_ashrrev_i32_e32 v9, 3, v2
	v_lshlrev_b32_e32 v2, 3, v2
	v_and_b32_e32 v2, 56, v2
	v_lshlrev_b32_e32 v5, 2, v9
	s_movk_i32 s0, 0x104
	v_mul_u32_u24_e32 v6, 0x104, v2
	v_lshlrev_b32_e32 v4, 2, v1
	v_mov_b32_e32 v3, 0
	v_mul_lo_u32 v7, v8, s0
	v_add_u32_e32 v15, v5, v6
	v_add_u32_e32 v10, 32, v8
	v_add_u32_e32 v11, 40, v8
	v_add_u32_e32 v12, 48, v8
	v_add_u32_e32 v13, 56, v8
	s_lshl_b32 s11, s10, 6
	s_lshl_b32 s12, s52, 6
	s_movk_i32 s13, 0x80
	v_add_u32_e32 v14, v4, v7
	v_lshlrev_b32_e32 v4, 1, v2
	v_mov_b32_e32 v5, v3
	v_add_u32_e32 v16, 0x400, v15
	s_branch .LBB0_119

; DEVI int otid() { int t = threadIdx.x; asm volatile("" : "+v"(t)); return t; }
; DEVI int obid() { int t = blockIdx.x; asm volatile("" : "+s"(t)); return t; }
; __device__ __forceinline__ void wconv(unsigned char* lds, const float* __restrict__ src, bf16_t* __restrict__ dst, int K, int Nsrc, int Ndst, int mode, int nbatch) {
;   float* tile = (float*)lds;
;   const int tid = otid();
;   const int tk = K >> 6, tn = Ndst >> 6, per = tk * tn, total = per * nbatch;
;   for (int it = obid(); it < total; it += gridDim.x) {
;     const int bi = it / per, rem = it - bi * per, kt = rem / tn, nt = rem - kt * tn;
;     const float* s = src + (size_t)bi * K * Nsrc; bf16_t* d = dst + (size_t)bi * Ndst * K;
;     const int nn = tid & 63, dcol = nt * 64 + nn;
;     int scol; float scale = 1.f;
;     if (mode == 0) scol = dcol < Nsrc ? dcol : -1;
;     else {
;       if (dcol < 2048) { scol = dcol; if (dcol >= 512 && dcol < 1024) scale = 0.08838834764831845f; }
;       else if (dcol < 3072) scol = dcol - 2048 + 3080;
;       else if (dcol < 4096) scol = dcol - 3072 + 2048;
;       else if (dcol < 5120) scol = dcol - 4096 + 4104;
;       else if (dcol < 5128) scol = dcol - 5120 + 3072;
;       else scol = -1;
;     }
;     __syncthreads();
; #pragma unroll
;     for (int i = 0; i < 8; ++i) {
;       const int kk = (tid >> 6) + 8 * i;
;       float v = 0.f; if (scol >= 0) v = s[(size_t)(kt * 64 + kk) * Nsrc + scol] * scale;
;       tile[kk * 65 + nn] = v;
; __global__ void __launch_bounds__(NT, 2) fwd_megakernel(Params p) {
;     ...
;   wconv(smem, p.ev_w_rx, (bf16_t*)(ws + OFF_WRX), 128, 128, 128, 0, 8);
.LBB0_127:
	v_readlane_b32 s0, v253, 2
	v_readlane_b32 s2, v253, 4
	v_readlane_b32 s3, v253, 5
	s_add_u32 s0, s2, 0x3650000
	v_writelane_b32 v254, s0, 14
	s_addc_u32 s0, s3, 0
	v_mov_b32_e32 v2, v128
	s_mov_b32 s10, s20
	s_cmp_lg_u32 s52, 0x100
	s_cbranch_scc1 .Lp0sh_2171
	s_add_i32 s10, s20, 0xd8
	s_and_b32 s10, s10, 0xff
.Lp0sh_2171:
	s_barrier
	v_writelane_b32 v254, s0, 16
	s_cmp_gt_i32 s10, 31
	v_readlane_b32 s1, v253, 3
	s_cbranch_scc1 .LBB0_138
	v_and_b32_e32 v1, 63, v2
	v_ashrrev_i32_e32 v8, 6, v2
	v_ashrrev_i32_e32 v9, 3, v2
	v_lshlrev_b32_e32 v2, 3, v2
	v_and_b32_e32 v2, 56, v2
	v_lshlrev_b32_e32 v5, 2, v9
	s_movk_i32 s0, 0x104
	v_mul_u32_u24_e32 v6, 0x104, v2
	v_lshlrev_b32_e32 v4, 2, v1
	v_mov_b32_e32 v3, 0
	v_mul_lo_u32 v7, v8, s0
	v_add_u32_e32 v15, v5, v6
	v_add_u32_e32 v10, 32, v8
	v_add_u32_e32 v11, 40, v8
	v_add_u32_e32 v12, 48, v8
	v_add_u32_e32 v13, 56, v8
	s_lshl_b32 s11, s10, 6
	s_lshl_b32 s12, s52, 6
	s_movk_i32 s13, 0x80
	v_add_u32_e32 v14, v4, v7
	v_lshlrev_b32_e32 v4, 1, v2
	v_mov_b32_e32 v5, v3
	v_add_u32_e32 v16, 0x400, v15
	s_branch .LBB0_130
